# baseline (speedup 1.0000x reference)
; #define WAIT_V(n) asm volatile("s_waitcnt vmcnt(" #n ")" ::: "memory")
; #define BAR __builtin_amdgcn_s_barrier()
;     ...
;   const int wid = tx >> 6, lane = tx & 63, wr = wid >> 2, wc = wid & 3, fr = lane & 15, fq = lane >> 4;
;   f32x4 acc[2][2][4][2] = {};
;   bf16x8 At[4][2], B0[2][2], B1[2][2];
;   const int nt = K / BK;
;   unsigned soff0, soff1;
;   { int _r, _c; stage_rc(tx * 16, _r, _c); soff0 = (unsigned)(_r * K + _c) * 2u;
;     stage_rc(tx * 16 + 8192, _r, _c); soff1 = (unsigned)(_r * K + _c) * 2u; }
;   STAGE(SB(0, 0), Bt, bcol, 0); STAGE(SA(0, 0), A, brow, 0);
;   STAGE(SB(0, 1), Bt, bcol1, 0); STAGE(SA(0, 1), A, brow + HALF, 0);
;   if (wr == 1) BAR;
;   WAIT_V(4); BAR;
;   STAGE(SB(1, 0), Bt, bcol, 1); STAGE(SA(1, 0), A, brow, 1); STAGE(SB(1, 1), Bt, bcol1, 1);
;   WAIT_V(6); BAR;
.LBB0_68:
	s_or_b64 exec, exec, s[12:13]
	v_add_u32_e32 v155, s54, v18
	v_add_u32_e32 v156, 0x2000, v155
	v_readfirstlane_b32 s12, v155
	v_lshl_add_u64 v[10:11], v[10:11], 0, s[24:25]
	s_mov_b32 m0, s12
	v_readfirstlane_b32 s12, v156
	v_add_u32_e32 v157, 0x8000, v147
	s_waitcnt vmcnt(4)
	s_barrier
	global_load_lds_dwordx4 v[10:11], off
	v_lshl_add_u64 v[8:9], v[8:9], 0, s[24:25]
	s_mov_b32 m0, s12
	v_readfirstlane_b32 s12, v157
	v_add_u32_e32 v158, 0xa000, v147
	global_load_lds_dwordx4 v[8:9], off
	v_lshl_add_u64 v[6:7], v[6:7], 0, s[24:25]
	s_mov_b32 m0, s12
	v_readfirstlane_b32 s12, v158
	v_add_u32_e32 v159, s55, v18
	global_load_lds_dwordx4 v[6:7], off
	v_lshl_add_u64 v[4:5], v[4:5], 0, s[24:25]
	s_mov_b32 m0, s12
	v_readfirstlane_b32 s12, v159
	v_add_u32_e32 v160, 0x2000, v159
	global_load_lds_dwordx4 v[4:5], off
	v_lshl_add_u64 v[2:3], v[2:3], 0, s[24:25]
	s_mov_b32 m0, s12
	v_readfirstlane_b32 s12, v160
	global_load_lds_dwordx4 v[2:3], off
	v_lshl_add_u64 v[0:1], v[0:1], 0, s[24:25]
	s_mov_b32 m0, s12
	v_and_b32_e32 v239, 15, v142
	global_load_lds_dwordx4 v[0:1], off
	v_lshlrev_b32_e32 v1, 2, v142
	v_and_b32_e32 v237, 48, v142
	v_lshlrev_b32_e32 v0, 6, v239
	v_and_b32_e32 v1, 32, v1
	v_bitop3_b32 v0, v0, v1, v237 bitop3:0x36
	v_add_u32_e32 v5, s33, v0
	v_add_u32_e32 v6, s53, v0
	v_add_u32_e32 v7, s54, v0
	v_add_u32_e32 v8, s55, v0
	v_add_u32_e32 v10, 0, v0
	v_lshlrev_b32_e32 v0, 6, v142
	v_and_or_b32 v0, v0, s56, v237
	v_xad_u32 v11, v0, v1, 0
	v_lshlrev_b32_e32 v0, 16, v12
	v_lshlrev_b32_e32 v2, 16, v14
	v_and_b32_e32 v0, 0xfffe0000, v0
	v_and_b32_e32 v2, 0xfffe0000, v2
	v_lshl_add_u32 v0, v13, 13, v0
	v_and_b32_e32 v1, 1, v12
	v_lshl_add_u32 v2, v16, 13, v2
	v_and_b32_e32 v3, 1, v14
	v_lshl_or_b32 v0, v1, 6, v0
	s_add_u32 s8, s20, s8
	v_lshl_or_b32 v2, v3, 6, v2
	v_lshl_add_u32 v0, v15, 1, v0
	v_mov_b32_e32 v1, v185
	s_addc_u32 s9, s21, s9
	v_lshl_add_u32 v2, v17, 1, v2
	v_mov_b32_e32 v3, v185
	v_lshl_add_u64 v[130:131], s[8:9], 0, v[0:1]
	v_lshl_add_u64 v[132:133], s[8:9], 0, v[2:3]
	s_add_u32 s8, s18, s10
	v_bfe_u32 v236, v143, 6, 2
	v_lshlrev_b32_e32 v9, 13, v238
	s_addc_u32 s9, s19, s11
	v_lshlrev_b32_e32 v4, 12, v236
	v_or_b32_e32 v18, 0x800, v9
	v_or_b32_e32 v19, 0x1000, v9
	v_or_b32_e32 v20, 0x1800, v9
	v_lshl_add_u64 v[134:135], s[8:9], 0, v[0:1]
	v_mov_b32_e32 v0, 0
	v_lshlrev_b32_e32 v138, 6, v238
	v_lshl_add_u64 v[136:137], s[8:9], 0, v[2:3]
	s_mov_b32 s10, -2
	s_mov_b64 s[8:9], 0
	v_add_u32_e32 v162, v5, v4
	v_add_u32_e32 v144, v10, v9
	v_add_u32_e32 v141, v11, v18
	v_add_u32_e32 v140, v11, v19
	v_add_u32_e32 v139, v11, v20
	v_add_u32_e32 v161, v6, v4
	v_add_u32_e32 v152, v7, v4
	v_add_u32_e32 v148, v8, v4
	v_mov_b32_e32 v1, v0
	v_mov_b32_e32 v2, v0
	v_mov_b32_e32 v3, v0
	v_mov_b32_e32 v4, v0
	v_mov_b32_e32 v5, v0
	v_mov_b32_e32 v6, v0
	v_mov_b32_e32 v7, v0
	v_mov_b32_e32 v8, v0
	v_mov_b32_e32 v9, v0
	v_mov_b32_e32 v10, v0
	v_mov_b32_e32 v11, v0
	v_mov_b32_e32 v12, v0
	v_mov_b32_e32 v13, v0
	v_mov_b32_e32 v14, v0
	v_mov_b32_e32 v15, v0
	v_mov_b32_e32 v16, v0
	v_mov_b32_e32 v17, v0
	v_mov_b32_e32 v18, v0
	v_mov_b32_e32 v19, v0
	v_mov_b32_e32 v20, v0
	v_mov_b32_e32 v21, v0
	v_mov_b32_e32 v22, v0
	v_mov_b32_e32 v23, v0
	v_mov_b32_e32 v24, v0
	v_mov_b32_e32 v25, v0
	v_mov_b32_e32 v26, v0
	v_mov_b32_e32 v27, v0
	v_mov_b32_e32 v28, v0
	v_mov_b32_e32 v29, v0
	v_mov_b32_e32 v30, v0
	v_mov_b32_e32 v31, v0
	v_mov_b32_e32 v32, v0
	v_mov_b32_e32 v33, v0
	v_mov_b32_e32 v34, v0
	v_mov_b32_e32 v35, v0
	v_mov_b32_e32 v36, v0
	v_mov_b32_e32 v37, v0
	v_mov_b32_e32 v38, v0
	v_mov_b32_e32 v39, v0
	v_mov_b32_e32 v40, v0
	v_mov_b32_e32 v41, v0
	v_mov_b32_e32 v42, v0
	v_mov_b32_e32 v43, v0
	v_mov_b32_e32 v44, v0
	v_mov_b32_e32 v45, v0
	v_mov_b32_e32 v46, v0
	v_mov_b32_e32 v47, v0
	v_mov_b32_e32 v48, v0
	v_mov_b32_e32 v49, v0
	v_mov_b32_e32 v50, v0
	v_mov_b32_e32 v51, v0
	v_mov_b32_e32 v52, v0
	v_mov_b32_e32 v53, v0
	v_mov_b32_e32 v54, v0
	v_mov_b32_e32 v55, v0
	v_mov_b32_e32 v56, v0
	v_mov_b32_e32 v57, v0
	v_mov_b32_e32 v58, v0
	v_mov_b32_e32 v59, v0
	v_mov_b32_e32 v60, v0
	v_mov_b32_e32 v61, v0
	v_mov_b32_e32 v62, v0
	v_mov_b32_e32 v63, v0
	v_mov_b32_e32 v64, v0
	v_mov_b32_e32 v65, v0
	v_mov_b32_e32 v66, v0
	v_mov_b32_e32 v67, v0
	v_mov_b32_e32 v68, v0
	v_mov_b32_e32 v69, v0
	v_mov_b32_e32 v70, v0
	v_mov_b32_e32 v71, v0
	v_mov_b32_e32 v72, v0
	v_mov_b32_e32 v73, v0
	v_mov_b32_e32 v74, v0
	v_mov_b32_e32 v75, v0
	v_mov_b32_e32 v76, v0
	v_mov_b32_e32 v77, v0
	v_mov_b32_e32 v78, v0
	v_mov_b32_e32 v79, v0
	v_mov_b32_e32 v80, v0
	v_mov_b32_e32 v81, v0
	v_mov_b32_e32 v82, v0
	v_mov_b32_e32 v83, v0
	v_mov_b32_e32 v84, v0
	v_mov_b32_e32 v85, v0
	v_mov_b32_e32 v86, v0
	v_mov_b32_e32 v87, v0
	v_mov_b32_e32 v88, v0
	v_mov_b32_e32 v89, v0
	v_mov_b32_e32 v90, v0
	v_mov_b32_e32 v91, v0
; #define WAIT_V(n) asm volatile("s_waitcnt vmcnt(" #n ")" ::: "memory")
; #define BAR __builtin_amdgcn_s_barrier()
;     ...
;   f32x4 acc[2][2][4][2] = {};
;   bf16x8 At[4][2], B0[2][2], B1[2][2];
;   const int nt = K / BK;
;   unsigned soff0, soff1;
;   { int _r, _c; stage_rc(tx * 16, _r, _c); soff0 = (unsigned)(_r * K + _c) * 2u;
;     stage_rc(tx * 16 + 8192, _r, _c); soff1 = (unsigned)(_r * K + _c) * 2u; }
;   STAGE(SB(0, 0), Bt, bcol, 0); STAGE(SA(0, 0), A, brow, 0);
;   STAGE(SB(0, 1), Bt, bcol1, 0); STAGE(SA(0, 1), A, brow + HALF, 0);
;   if (wr == 1) BAR;
;   WAIT_V(4); BAR;
;   STAGE(SB(1, 0), Bt, bcol, 1); STAGE(SA(1, 0), A, brow, 1); STAGE(SB(1, 1), Bt, bcol1, 1);
;   WAIT_V(6); BAR;
;   for (int t = 0; t < nt - 2; t += 2) {
	v_mov_b32_e32 v92, v0
	v_mov_b32_e32 v93, v0
	v_mov_b32_e32 v94, v0
	v_mov_b32_e32 v95, v0
	v_mov_b32_e32 v96, v0
	v_mov_b32_e32 v97, v0
	v_mov_b32_e32 v98, v0
	v_mov_b32_e32 v99, v0
	v_mov_b32_e32 v100, v0
	v_mov_b32_e32 v101, v0
	v_mov_b32_e32 v102, v0
	v_mov_b32_e32 v103, v0
	v_mov_b32_e32 v104, v0
	v_mov_b32_e32 v105, v0
	v_mov_b32_e32 v106, v0
	v_mov_b32_e32 v107, v0
	v_mov_b32_e32 v108, v0
	v_mov_b32_e32 v109, v0
	v_mov_b32_e32 v110, v0
	v_mov_b32_e32 v111, v0
	v_mov_b32_e32 v112, v0
	v_mov_b32_e32 v113, v0
	v_mov_b32_e32 v114, v0
	v_mov_b32_e32 v115, v0
	v_mov_b32_e32 v116, v0
	v_mov_b32_e32 v117, v0
	v_mov_b32_e32 v118, v0
	v_mov_b32_e32 v119, v0
	v_mov_b32_e32 v120, v0
	v_mov_b32_e32 v121, v0
	v_mov_b32_e32 v122, v0
	v_mov_b32_e32 v123, v0
	v_mov_b32_e32 v124, v0
	v_mov_b32_e32 v125, v0
	v_mov_b32_e32 v126, v0
	v_mov_b32_e32 v127, v0
	v_or_b32_e32 v235, v138, v239
	v_readfirstlane_b32 s11, v147
	v_writelane_b32 v254, s64, 0
	v_writelane_b32 v254, s65, 1
	v_writelane_b32 v254, s66, 2
	v_writelane_b32 v254, s67, 3
	v_writelane_b32 v254, s68, 4
	v_writelane_b32 v254, s69, 5
	v_writelane_b32 v254, s70, 6
	v_writelane_b32 v254, s71, 7
	v_writelane_b32 v254, s72, 8
	v_writelane_b32 v254, s73, 9
	v_writelane_b32 v254, s74, 10
	v_writelane_b32 v254, s75, 11
	v_writelane_b32 v254, s76, 12
	v_writelane_b32 v254, s77, 13
	v_writelane_b32 v254, s78, 14
	v_writelane_b32 v254, s79, 15
	v_writelane_b32 v254, s80, 16
	v_writelane_b32 v254, s81, 17
	v_writelane_b32 v254, s82, 18
	v_writelane_b32 v254, s83, 19
	v_writelane_b32 v254, s84, 20
	v_writelane_b32 v254, s85, 21
	v_writelane_b32 v254, s86, 22
	v_writelane_b32 v254, s87, 23
	v_writelane_b32 v254, s88, 24
	v_writelane_b32 v254, s89, 25
	v_writelane_b32 v254, s90, 26
	v_writelane_b32 v254, s91, 27
	v_writelane_b32 v254, s92, 28
	v_writelane_b32 v254, s93, 29
	v_writelane_b32 v254, s94, 30
	v_writelane_b32 v254, s95, 31
	v_readfirstlane_b32 s64, v134
	v_readfirstlane_b32 s65, v135
	v_readfirstlane_b32 s66, v136
	v_readfirstlane_b32 s67, v137
	v_readfirstlane_b32 s68, v130
	v_readfirstlane_b32 s69, v131
	v_readfirstlane_b32 s70, v132
	v_readfirstlane_b32 s71, v133
	v_readfirstlane_b32 s72, v134
	v_readfirstlane_b32 s73, v135
	v_readfirstlane_b32 s74, v136
	v_readfirstlane_b32 s75, v137
	v_readfirstlane_b32 s76, v130
	v_readfirstlane_b32 s77, v131
	v_readfirstlane_b32 s78, v132
	v_readfirstlane_b32 s79, v133
	v_readfirstlane_b32 s80, v134
	v_readfirstlane_b32 s81, v135
	v_readfirstlane_b32 s82, v136
	v_readfirstlane_b32 s83, v137
	v_readfirstlane_b32 s84, v130
	v_readfirstlane_b32 s85, v131
	v_readfirstlane_b32 s86, v132
	v_readfirstlane_b32 s87, v133
	v_readfirstlane_b32 s88, v134
	v_readfirstlane_b32 s89, v135
	v_readfirstlane_b32 s90, v136
	v_readfirstlane_b32 s91, v137
	v_readfirstlane_b32 s92, v130
	v_readfirstlane_b32 s93, v131
	v_readfirstlane_b32 s94, v132
	v_readfirstlane_b32 s95, v133
	s_nop 3
	v_subrev_u32_e32 v151, s64, v134
	v_subrev_u32_e32 v153, s66, v136
	v_subrev_u32_e32 v149, s68, v130
	v_subrev_u32_e32 v150, s70, v132
	s_add_u32 s64, s64, s8
	s_addc_u32 s65, s65, s9
	s_add_u32 s64, s64, s26
	s_addc_u32 s65, s65, s27
	s_add_u32 s66, s66, s8
	s_addc_u32 s67, s67, s9
	s_add_u32 s66, s66, s26
	s_addc_u32 s67, s67, s27
	s_add_u32 s68, s68, s8
	s_addc_u32 s69, s69, s9
	s_add_u32 s68, s68, s28
	s_addc_u32 s69, s69, s29
	s_add_u32 s70, s70, s8
	s_addc_u32 s71, s71, s9
	s_add_u32 s70, s70, s28
	s_addc_u32 s71, s71, s29
	s_add_u32 s72, s72, s8
	s_addc_u32 s73, s73, s9
	s_add_u32 s72, s72, s28
	s_addc_u32 s73, s73, s29
	s_add_u32 s74, s74, s8
	s_addc_u32 s75, s75, s9
	s_add_u32 s74, s74, s28
	s_addc_u32 s75, s75, s29
	s_add_u32 s76, s76, s8
	s_addc_u32 s77, s77, s9
	s_add_u32 s76, s76, s30
	s_addc_u32 s77, s77, s31
	s_add_u32 s78, s78, s8
	s_addc_u32 s79, s79, s9
	s_add_u32 s78, s78, s30
	s_addc_u32 s79, s79, s31
	s_add_u32 s80, s80, s8
	s_addc_u32 s81, s81, s9
	s_add_u32 s80, s80, s30
	s_addc_u32 s81, s81, s31
	s_add_u32 s82, s82, s8
	s_addc_u32 s83, s83, s9
	s_add_u32 s82, s82, s30
	s_addc_u32 s83, s83, s31
	s_add_u32 s84, s84, s8
	s_addc_u32 s85, s85, s9
	s_add_u32 s84, s84, s34
	s_addc_u32 s85, s85, s35
	s_add_u32 s86, s86, s8
	s_addc_u32 s87, s87, s9
	s_add_u32 s86, s86, s34
	s_addc_u32 s87, s87, s35
	s_add_u32 s88, s88, s8
	s_addc_u32 s89, s89, s9
	s_add_u32 s88, s88, s34
	s_addc_u32 s89, s89, s35
	s_add_u32 s90, s90, s8
	s_addc_u32 s91, s91, s9
	s_add_u32 s90, s90, s34
	s_addc_u32 s91, s91, s35
	s_add_u32 s92, s92, s8
	s_addc_u32 s93, s93, s9
	s_add_u32 s92, s92, s36
	s_addc_u32 s93, s93, s37
	s_add_u32 s94, s94, s8
	s_addc_u32 s95, s95, s9
	s_add_u32 s94, s94, s36
	s_addc_u32 s95, s95, s37
	v_add_u32_e32 v163, 0xc000, v147
	v_add_u32_e32 v164, 0xe000, v147
	s_waitcnt vmcnt(6)
	s_barrier

; #define WAIT_V(n) asm volatile("s_waitcnt vmcnt(" #n ")" ::: "memory")
; #define BAR __builtin_amdgcn_s_barrier()
;     ...
;   const int wid = tx >> 6, lane = tx & 63, wr = wid >> 2, wc = wid & 3, fr = lane & 15, fq = lane >> 4;
;   f32x4 acc[2][2][4][2] = {};
;   bf16x8 At[4][2], B0[2][2], B1[2][2];
;   const int nt = K / BK;
;   unsigned soff0, soff1;
;   { int _r, _c; stage_rc(tx * 16, _r, _c); soff0 = (unsigned)(_r * K + _c) * 2u;
;     stage_rc(tx * 16 + 8192, _r, _c); soff1 = (unsigned)(_r * K + _c) * 2u; }
;   STAGE(SB(0, 0), Bt, bcol, 0); STAGE(SA(0, 0), A, brow, 0);
;   STAGE(SB(0, 1), Bt, bcol1, 0); STAGE(SA(0, 1), A, brow + HALF, 0);
;   if (wr == 1) BAR;
;   WAIT_V(4); BAR;
;   STAGE(SB(1, 0), Bt, bcol, 1); STAGE(SA(1, 0), A, brow, 1); STAGE(SB(1, 1), Bt, bcol1, 1);
;   WAIT_V(6); BAR;
.LBB0_1141:
	s_or_b64 exec, exec, s[34:35]
	v_add_u32_e32 v162, s38, v18
	v_add_u32_e32 v163, 0x2000, v162
	v_readfirstlane_b32 s25, v162
	v_lshl_add_u64 v[10:11], v[10:11], 0, s[12:13]
	s_mov_b32 m0, s25
	v_readfirstlane_b32 s25, v163
	v_add_u32_e32 v164, 0x8000, v154
	s_waitcnt vmcnt(4)
	s_barrier
	global_load_lds_dwordx4 v[10:11], off
	v_lshl_add_u64 v[8:9], v[8:9], 0, s[12:13]
	s_mov_b32 m0, s25
	v_readfirstlane_b32 s25, v164
	v_add_u32_e32 v165, 0xa000, v154
	global_load_lds_dwordx4 v[8:9], off
	v_lshl_add_u64 v[6:7], v[6:7], 0, s[12:13]
	s_mov_b32 m0, s25
	v_readfirstlane_b32 s25, v165
	v_add_u32_e32 v166, s39, v18
	global_load_lds_dwordx4 v[6:7], off
	v_lshl_add_u64 v[4:5], v[4:5], 0, s[12:13]
	s_mov_b32 m0, s25
	v_readfirstlane_b32 s25, v166
	v_add_u32_e32 v167, 0x2000, v166
	global_load_lds_dwordx4 v[4:5], off
	v_lshl_add_u64 v[2:3], v[2:3], 0, s[12:13]
	s_mov_b32 m0, s25
	v_readfirstlane_b32 s25, v167
	global_load_lds_dwordx4 v[2:3], off
	v_lshl_add_u64 v[0:1], v[0:1], 0, s[12:13]
	s_mov_b32 m0, s25
	v_and_b32_e32 v142, 15, v140
	global_load_lds_dwordx4 v[0:1], off
	v_lshlrev_b32_e32 v2, 2, v140
	v_and_b32_e32 v0, 48, v140
	v_lshlrev_b32_e32 v1, 6, v142
	v_and_b32_e32 v2, 32, v2
	v_bitop3_b32 v1, v1, v2, v0 bitop3:0x36
	v_add_u32_e32 v5, s36, v1
	v_add_u32_e32 v6, s37, v1
	v_add_u32_e32 v7, s38, v1
	v_add_u32_e32 v8, s39, v1
	v_add_u32_e32 v10, 0, v1
	v_lshlrev_b32_e32 v1, 6, v140
	v_and_or_b32 v0, v1, s40, v0
	v_xad_u32 v11, v0, v2, 0
	v_lshlrev_b32_e32 v0, 16, v12
	v_lshlrev_b32_e32 v2, 16, v14
	v_and_b32_e32 v0, 0xfffe0000, v0
	v_and_b32_e32 v2, 0xfffe0000, v2
	v_lshl_add_u32 v0, v13, 13, v0
	v_and_b32_e32 v1, 1, v12
	v_lshl_add_u32 v2, v16, 13, v2
	v_and_b32_e32 v3, 1, v14
	v_lshl_or_b32 v0, v1, 6, v0
	s_add_u32 s30, s8, s30
	v_lshl_or_b32 v2, v3, 6, v2
	v_lshl_add_u32 v0, v15, 1, v0
	v_mov_b32_e32 v1, v137
	s_addc_u32 s31, s9, s31
	v_lshl_add_u32 v2, v17, 1, v2
	v_mov_b32_e32 v3, v137
	v_lshl_add_u64 v[130:131], s[30:31], 0, v[0:1]
	v_lshl_add_u64 v[132:133], s[30:31], 0, v[2:3]
	s_add_i32 s30, s46, s47
	s_ashr_i32 s31, s30, 31
	s_lshl_b64 s[30:31], s[30:31], 13
	s_add_u32 s30, s4, s30
	v_bfe_u32 v141, v150, 6, 2
	v_lshlrev_b32_e32 v9, 13, v19
	s_addc_u32 s31, s5, s31
	v_lshlrev_b32_e32 v4, 12, v141
	v_lshlrev_b32_e32 v143, 6, v19
	v_or_b32_e32 v18, 0x800, v9
	v_or_b32_e32 v19, 0x1000, v9
	v_or_b32_e32 v20, 0x1800, v9
	v_lshl_add_u64 v[134:135], s[30:31], 0, v[0:1]
	v_mov_b32_e32 v0, 0
	v_or_b32_e32 v151, v143, v142
	v_lshl_add_u64 v[138:139], s[30:31], 0, v[2:3]
	s_mov_b32 s25, -2
	s_mov_b64 s[30:31], 0
	v_add_u32_e32 v169, v5, v4
	v_add_u32_e32 v147, v10, v9
	v_add_u32_e32 v146, v11, v18
	v_add_u32_e32 v145, v11, v19
	v_add_u32_e32 v144, v11, v20
	v_add_u32_e32 v168, v6, v4
	v_add_u32_e32 v160, v7, v4
	v_add_u32_e32 v155, v8, v4
	v_mov_b32_e32 v1, v0
	v_mov_b32_e32 v2, v0
	v_mov_b32_e32 v3, v0
	v_mov_b32_e32 v4, v0
	v_mov_b32_e32 v5, v0
	v_mov_b32_e32 v6, v0
	v_mov_b32_e32 v7, v0
	v_mov_b32_e32 v8, v0
	v_mov_b32_e32 v9, v0
	v_mov_b32_e32 v10, v0
	v_mov_b32_e32 v11, v0
	v_mov_b32_e32 v12, v0
	v_mov_b32_e32 v13, v0
	v_mov_b32_e32 v14, v0
	v_mov_b32_e32 v15, v0
	v_mov_b32_e32 v16, v0
	v_mov_b32_e32 v17, v0
	v_mov_b32_e32 v18, v0
	v_mov_b32_e32 v19, v0
	v_mov_b32_e32 v20, v0
	v_mov_b32_e32 v21, v0
	v_mov_b32_e32 v22, v0
	v_mov_b32_e32 v23, v0
	v_mov_b32_e32 v24, v0
	v_mov_b32_e32 v25, v0
	v_mov_b32_e32 v26, v0
	v_mov_b32_e32 v27, v0
	v_mov_b32_e32 v28, v0
	v_mov_b32_e32 v29, v0
	v_mov_b32_e32 v30, v0
	v_mov_b32_e32 v31, v0
	v_mov_b32_e32 v32, v0
	v_mov_b32_e32 v33, v0
	v_mov_b32_e32 v34, v0
	v_mov_b32_e32 v35, v0
	v_mov_b32_e32 v36, v0
	v_mov_b32_e32 v37, v0
	v_mov_b32_e32 v38, v0
	v_mov_b32_e32 v39, v0
	v_mov_b32_e32 v40, v0
	v_mov_b32_e32 v41, v0
	v_mov_b32_e32 v42, v0
	v_mov_b32_e32 v43, v0
	v_mov_b32_e32 v44, v0
	v_mov_b32_e32 v45, v0
	v_mov_b32_e32 v46, v0
	v_mov_b32_e32 v47, v0
	v_mov_b32_e32 v48, v0
	v_mov_b32_e32 v49, v0
	v_mov_b32_e32 v50, v0
	v_mov_b32_e32 v51, v0
	v_mov_b32_e32 v52, v0
	v_mov_b32_e32 v53, v0
	v_mov_b32_e32 v54, v0
	v_mov_b32_e32 v55, v0
	v_mov_b32_e32 v56, v0
	v_mov_b32_e32 v57, v0
	v_mov_b32_e32 v58, v0
	v_mov_b32_e32 v59, v0
	v_mov_b32_e32 v60, v0
	v_mov_b32_e32 v61, v0
	v_mov_b32_e32 v62, v0
	v_mov_b32_e32 v63, v0
	v_mov_b32_e32 v64, v0
	v_mov_b32_e32 v65, v0
	v_mov_b32_e32 v66, v0
	v_mov_b32_e32 v67, v0
	v_mov_b32_e32 v68, v0
	v_mov_b32_e32 v69, v0
	v_mov_b32_e32 v70, v0
	v_mov_b32_e32 v71, v0
	v_mov_b32_e32 v72, v0
	v_mov_b32_e32 v73, v0
	v_mov_b32_e32 v74, v0
	v_mov_b32_e32 v75, v0
	v_mov_b32_e32 v76, v0
	v_mov_b32_e32 v77, v0
	v_mov_b32_e32 v78, v0
	v_mov_b32_e32 v79, v0
	v_mov_b32_e32 v80, v0
	v_mov_b32_e32 v81, v0
	v_mov_b32_e32 v82, v0
	v_mov_b32_e32 v83, v0
	v_mov_b32_e32 v84, v0
	v_mov_b32_e32 v85, v0
	v_mov_b32_e32 v86, v0
	v_mov_b32_e32 v87, v0
	v_mov_b32_e32 v88, v0
; #define WAIT_V(n) asm volatile("s_waitcnt vmcnt(" #n ")" ::: "memory")
; #define BAR __builtin_amdgcn_s_barrier()
;     ...
;   f32x4 acc[2][2][4][2] = {};
;   bf16x8 At[4][2], B0[2][2], B1[2][2];
;   const int nt = K / BK;
;   unsigned soff0, soff1;
;   { int _r, _c; stage_rc(tx * 16, _r, _c); soff0 = (unsigned)(_r * K + _c) * 2u;
;     stage_rc(tx * 16 + 8192, _r, _c); soff1 = (unsigned)(_r * K + _c) * 2u; }
;   STAGE(SB(0, 0), Bt, bcol, 0); STAGE(SA(0, 0), A, brow, 0);
;   STAGE(SB(0, 1), Bt, bcol1, 0); STAGE(SA(0, 1), A, brow + HALF, 0);
;   if (wr == 1) BAR;
;   WAIT_V(4); BAR;
;   STAGE(SB(1, 0), Bt, bcol, 1); STAGE(SA(1, 0), A, brow, 1); STAGE(SB(1, 1), Bt, bcol1, 1);
;   WAIT_V(6); BAR;
;   for (int t = 0; t < nt - 2; t += 2) {
	v_mov_b32_e32 v89, v0
	v_mov_b32_e32 v90, v0
	v_mov_b32_e32 v91, v0
	v_mov_b32_e32 v92, v0
	v_mov_b32_e32 v93, v0
	v_mov_b32_e32 v94, v0
	v_mov_b32_e32 v95, v0
	v_mov_b32_e32 v96, v0
	v_mov_b32_e32 v97, v0
	v_mov_b32_e32 v98, v0
	v_mov_b32_e32 v99, v0
	v_mov_b32_e32 v100, v0
	v_mov_b32_e32 v101, v0
	v_mov_b32_e32 v102, v0
	v_mov_b32_e32 v103, v0
	v_mov_b32_e32 v104, v0
	v_mov_b32_e32 v105, v0
	v_mov_b32_e32 v106, v0
	v_mov_b32_e32 v107, v0
	v_mov_b32_e32 v108, v0
	v_mov_b32_e32 v109, v0
	v_mov_b32_e32 v110, v0
	v_mov_b32_e32 v111, v0
	v_mov_b32_e32 v112, v0
	v_mov_b32_e32 v113, v0
	v_mov_b32_e32 v114, v0
	v_mov_b32_e32 v115, v0
	v_mov_b32_e32 v116, v0
	v_mov_b32_e32 v117, v0
	v_mov_b32_e32 v118, v0
	v_mov_b32_e32 v119, v0
	v_mov_b32_e32 v120, v0
	v_mov_b32_e32 v121, v0
	v_mov_b32_e32 v122, v0
	v_mov_b32_e32 v123, v0
	v_mov_b32_e32 v124, v0
	v_mov_b32_e32 v125, v0
	v_mov_b32_e32 v126, v0
	v_mov_b32_e32 v127, v0
	v_readfirstlane_b32 s27, v154
	v_writelane_b32 v254, s64, 0
	v_writelane_b32 v254, s65, 1
	v_writelane_b32 v254, s66, 2
	v_writelane_b32 v254, s67, 3
	v_writelane_b32 v254, s68, 4
	v_writelane_b32 v254, s69, 5
	v_writelane_b32 v254, s70, 6
	v_writelane_b32 v254, s71, 7
	v_writelane_b32 v254, s72, 8
	v_writelane_b32 v254, s73, 9
	v_writelane_b32 v254, s74, 10
	v_writelane_b32 v254, s75, 11
	v_writelane_b32 v254, s76, 12
	v_writelane_b32 v254, s77, 13
	v_writelane_b32 v254, s78, 14
	v_writelane_b32 v254, s79, 15
	v_writelane_b32 v254, s80, 16
	v_writelane_b32 v254, s81, 17
	v_writelane_b32 v254, s82, 18
	v_writelane_b32 v254, s83, 19
	v_writelane_b32 v254, s84, 20
	v_writelane_b32 v254, s85, 21
	v_writelane_b32 v254, s86, 22
	v_writelane_b32 v254, s87, 23
	v_writelane_b32 v254, s88, 24
	v_writelane_b32 v254, s89, 25
	v_writelane_b32 v254, s90, 26
	v_writelane_b32 v254, s91, 27
	v_writelane_b32 v254, s92, 28
	v_writelane_b32 v254, s93, 29
	v_writelane_b32 v254, s94, 30
	v_writelane_b32 v254, s95, 31
	v_readfirstlane_b32 s64, v134
	v_readfirstlane_b32 s65, v135
	v_readfirstlane_b32 s66, v138
	v_readfirstlane_b32 s67, v139
	v_readfirstlane_b32 s68, v130
	v_readfirstlane_b32 s69, v131
	v_readfirstlane_b32 s70, v132
	v_readfirstlane_b32 s71, v133
	v_readfirstlane_b32 s72, v134
	v_readfirstlane_b32 s73, v135
	v_readfirstlane_b32 s74, v138
	v_readfirstlane_b32 s75, v139
	v_readfirstlane_b32 s76, v130
	v_readfirstlane_b32 s77, v131
	v_readfirstlane_b32 s78, v132
	v_readfirstlane_b32 s79, v133
	v_readfirstlane_b32 s80, v134
	v_readfirstlane_b32 s81, v135
	v_readfirstlane_b32 s82, v138
	v_readfirstlane_b32 s83, v139
	v_readfirstlane_b32 s84, v130
	v_readfirstlane_b32 s85, v131
	v_readfirstlane_b32 s86, v132
	v_readfirstlane_b32 s87, v133
	v_readfirstlane_b32 s88, v134
	v_readfirstlane_b32 s89, v135
	v_readfirstlane_b32 s90, v138
	v_readfirstlane_b32 s91, v139
	v_readfirstlane_b32 s92, v130
	v_readfirstlane_b32 s93, v131
	v_readfirstlane_b32 s94, v132
	v_readfirstlane_b32 s95, v133
	s_nop 3
	v_subrev_u32_e32 v158, s64, v134
	v_subrev_u32_e32 v159, s66, v138
	v_subrev_u32_e32 v156, s68, v130
	v_subrev_u32_e32 v157, s70, v132
	s_add_u32 s64, s64, s30
	s_addc_u32 s65, s65, s31
	s_add_u32 s64, s64, s14
	s_addc_u32 s65, s65, s15
	s_add_u32 s66, s66, s30
	s_addc_u32 s67, s67, s31
	s_add_u32 s66, s66, s14
	s_addc_u32 s67, s67, s15
	s_add_u32 s68, s68, s30
	s_addc_u32 s69, s69, s31
	s_add_u32 s68, s68, s16
	s_addc_u32 s69, s69, s17
	s_add_u32 s70, s70, s30
	s_addc_u32 s71, s71, s31
	s_add_u32 s70, s70, s16
	s_addc_u32 s71, s71, s17
	s_add_u32 s72, s72, s30
	s_addc_u32 s73, s73, s31
	s_add_u32 s72, s72, s16
	s_addc_u32 s73, s73, s17
	s_add_u32 s74, s74, s30
	s_addc_u32 s75, s75, s31
	s_add_u32 s74, s74, s16
	s_addc_u32 s75, s75, s17
	s_add_u32 s76, s76, s30
	s_addc_u32 s77, s77, s31
	s_add_u32 s76, s76, s18
	s_addc_u32 s77, s77, s19
	s_add_u32 s78, s78, s30
	s_addc_u32 s79, s79, s31
	s_add_u32 s78, s78, s18
	s_addc_u32 s79, s79, s19
	s_add_u32 s80, s80, s30
	s_addc_u32 s81, s81, s31
	s_add_u32 s80, s80, s18
	s_addc_u32 s81, s81, s19
	s_add_u32 s82, s82, s30
	s_addc_u32 s83, s83, s31
	s_add_u32 s82, s82, s18
	s_addc_u32 s83, s83, s19
	s_add_u32 s84, s84, s30
	s_addc_u32 s85, s85, s31
	s_add_u32 s84, s84, s20
	s_addc_u32 s85, s85, s21
	s_add_u32 s86, s86, s30
	s_addc_u32 s87, s87, s31
	s_add_u32 s86, s86, s20
	s_addc_u32 s87, s87, s21
	s_add_u32 s88, s88, s30
	s_addc_u32 s89, s89, s31
	s_add_u32 s88, s88, s20
	s_addc_u32 s89, s89, s21
	s_add_u32 s90, s90, s30
	s_addc_u32 s91, s91, s31
	s_add_u32 s90, s90, s20
	s_addc_u32 s91, s91, s21
	s_add_u32 s92, s92, s30
	s_addc_u32 s93, s93, s31
	s_add_u32 s92, s92, s22
	s_addc_u32 s93, s93, s23
	s_add_u32 s94, s94, s30
	s_addc_u32 s95, s95, s31
	s_add_u32 s94, s94, s22
	s_addc_u32 s95, s95, s23
	v_add_u32_e32 v170, 0xc000, v154
	v_add_u32_e32 v171, 0xe000, v154
	s_waitcnt vmcnt(6)
	s_barrier

; #define WAIT_V(n) asm volatile("s_waitcnt vmcnt(" #n ")" ::: "memory")
; #define BAR __builtin_amdgcn_s_barrier()
;     ...
;   const int wid = tx >> 6, lane = tx & 63, wr = wid >> 2, wc = wid & 3, fr = lane & 15, fq = lane >> 4;
;   f32x4 acc[2][2][4][2] = {};
;   bf16x8 At[4][2], B0[2][2], B1[2][2];
;   const int nt = K / BK;
;   unsigned soff0, soff1;
;   { int _r, _c; stage_rc(tx * 16, _r, _c); soff0 = (unsigned)(_r * K + _c) * 2u;
;     stage_rc(tx * 16 + 8192, _r, _c); soff1 = (unsigned)(_r * K + _c) * 2u; }
;   STAGE(SB(0, 0), Bt, bcol, 0); STAGE(SA(0, 0), A, brow, 0);
;   STAGE(SB(0, 1), Bt, bcol1, 0); STAGE(SA(0, 1), A, brow + HALF, 0);
;   if (wr == 1) BAR;
;   WAIT_V(4); BAR;
;   STAGE(SB(1, 0), Bt, bcol, 1); STAGE(SA(1, 0), A, brow, 1); STAGE(SB(1, 1), Bt, bcol1, 1);
;   WAIT_V(6); BAR;
.LBB0_1235:
	s_or_b64 exec, exec, s[44:45]
	v_add_u32_e32 v162, s59, v15
	v_add_u32_e32 v163, 0x2000, v162
	v_readfirstlane_b32 s4, v162
	v_lshl_add_u64 v[6:7], v[6:7], 0, s[22:23]
	s_mov_b32 m0, s4
	v_readfirstlane_b32 s4, v163
	v_add_u32_e32 v164, 0x8000, v154
	s_waitcnt vmcnt(4)
	s_barrier
	global_load_lds_dwordx4 v[6:7], off
	v_lshl_add_u64 v[4:5], v[4:5], 0, s[22:23]
	s_mov_b32 m0, s4
	v_readfirstlane_b32 s4, v164
	v_add_u32_e32 v165, 0xa000, v154
	global_load_lds_dwordx4 v[4:5], off
	v_lshl_add_u64 v[2:3], v[2:3], 0, s[22:23]
	s_mov_b32 m0, s4
	v_readfirstlane_b32 s4, v165
	global_load_lds_dwordx4 v[2:3], off
	s_mov_b32 m0, s4
	s_add_u32 s4, s7, 0x5600080
	v_add_u32_e32 v168, s60, v15
	v_lshl_add_u64 v[0:1], v[0:1], 0, s[22:23]
	s_addc_u32 s5, s47, 0
	v_readfirstlane_b32 s7, v168
	global_load_lds_dwordx4 v[0:1], off
	v_lshl_add_u64 v[0:1], s[4:5], 0, v[148:149]
	s_mov_b32 m0, s7
	v_add_u32_e32 v171, 0x2000, v168
	global_load_lds_dwordx4 v[0:1], off
	v_lshl_add_u64 v[0:1], s[4:5], 0, v[128:129]
	v_readfirstlane_b32 s4, v171
	s_mov_b32 m0, s4
	v_and_b32_e32 v169, 15, v9
	global_load_lds_dwordx4 v[0:1], off
	v_bfe_u32 v146, v9, 4, 2
	v_lshlrev_b32_e32 v1, 2, v9
	v_lshlrev_b32_e32 v147, 4, v146
	v_lshlrev_b32_e32 v0, 6, v169
	v_and_b32_e32 v1, 32, v1
	v_bitop3_b32 v0, v147, v1, v0 bitop3:0x36
	v_add_u32_e32 v5, s33, v0
	v_add_u32_e32 v6, s58, v0
	v_add_u32_e32 v7, s59, v0
	v_add_u32_e32 v15, s60, v0
	v_add_u32_e32 v17, 0, v0
	v_lshlrev_b32_e32 v0, 6, v9
	v_and_or_b32 v0, v0, s83, v147
	v_xad_u32 v9, v0, v1, 0
	v_lshlrev_b32_e32 v0, 16, v8
	v_lshlrev_b32_e32 v2, 16, v11
	v_and_b32_e32 v0, 0xfffe0000, v0
	v_and_b32_e32 v2, 0xfffe0000, v2
	v_lshl_add_u32 v0, v10, 13, v0
	v_and_b32_e32 v1, 1, v8
	v_lshl_add_u32 v2, v13, 13, v2
	v_and_b32_e32 v3, 1, v11
	v_lshl_or_b32 v0, v1, 6, v0
	s_add_u32 s4, s20, s12
	v_lshl_or_b32 v2, v3, 6, v2
	v_lshl_add_u32 v0, v12, 1, v0
	v_mov_b32_e32 v1, v149
	s_addc_u32 s5, s21, s13
	v_lshl_add_u32 v2, v14, 1, v2
	v_mov_b32_e32 v3, v149
	v_lshl_add_u64 v[130:131], s[4:5], 0, v[0:1]
	v_lshl_add_u64 v[132:133], s[4:5], 0, v[2:3]
	s_add_u32 s4, s18, s14
	s_addc_u32 s5, s19, s15
	v_lshl_add_u64 v[134:135], s[4:5], 0, v[0:1]
	v_lshl_add_u64 v[136:137], s[4:5], 0, v[2:3]
	s_add_u32 s4, s20, s42
	v_bfe_u32 v144, v145, 6, 2
	v_lshlrev_b32_e32 v16, 13, v167
	s_addc_u32 s5, s21, s43
	v_lshlrev_b32_e32 v4, 12, v144
	v_or_b32_e32 v18, 0x800, v16
	v_or_b32_e32 v19, 0x1000, v16
	v_or_b32_e32 v20, 0x1800, v16
	v_lshl_add_u64 v[138:139], s[4:5], 0, v[0:1]
	v_mov_b32_e32 v0, 0
	v_lshlrev_b32_e32 v170, 6, v167
	v_lshl_add_u64 v[140:141], s[4:5], 0, v[2:3]
	s_mov_b32 s7, -2
	s_mov_b64 s[4:5], 0
	v_add_u32_e32 v173, v5, v4
	v_add_u32_e32 v153, v17, v16
	v_add_u32_e32 v152, v9, v18
	v_add_u32_e32 v151, v9, v19
	v_add_u32_e32 v150, v9, v20
	v_add_u32_e32 v172, v6, v4
	v_add_u32_e32 v161, v7, v4
	v_add_u32_e32 v156, v15, v4
	v_mov_b32_e32 v1, v0
	v_mov_b32_e32 v2, v0
	v_mov_b32_e32 v3, v0
	v_mov_b32_e32 v4, v0
	v_mov_b32_e32 v5, v0
	v_mov_b32_e32 v6, v0
	v_mov_b32_e32 v7, v0
	v_mov_b32_e32 v8, v0
	v_mov_b32_e32 v9, v0
	v_mov_b32_e32 v10, v0
	v_mov_b32_e32 v11, v0
	v_mov_b32_e32 v12, v0
	v_mov_b32_e32 v13, v0
	v_mov_b32_e32 v14, v0
	v_mov_b32_e32 v15, v0
	v_mov_b32_e32 v16, v0
	v_mov_b32_e32 v17, v0
	v_mov_b32_e32 v18, v0
	v_mov_b32_e32 v19, v0
	v_mov_b32_e32 v20, v0
	v_mov_b32_e32 v21, v0
	v_mov_b32_e32 v22, v0
	v_mov_b32_e32 v23, v0
	v_mov_b32_e32 v24, v0
	v_mov_b32_e32 v25, v0
	v_mov_b32_e32 v26, v0
	v_mov_b32_e32 v27, v0
	v_mov_b32_e32 v28, v0
	v_mov_b32_e32 v29, v0
	v_mov_b32_e32 v30, v0
	v_mov_b32_e32 v31, v0
	v_mov_b32_e32 v32, v0
	v_mov_b32_e32 v33, v0
	v_mov_b32_e32 v34, v0
	v_mov_b32_e32 v35, v0
	v_mov_b32_e32 v36, v0
	v_mov_b32_e32 v37, v0
	v_mov_b32_e32 v38, v0
	v_mov_b32_e32 v39, v0
	v_mov_b32_e32 v40, v0
	v_mov_b32_e32 v41, v0
	v_mov_b32_e32 v42, v0
	v_mov_b32_e32 v43, v0
	v_mov_b32_e32 v44, v0
	v_mov_b32_e32 v45, v0
	v_mov_b32_e32 v46, v0
	v_mov_b32_e32 v47, v0
	v_mov_b32_e32 v48, v0
	v_mov_b32_e32 v49, v0
	v_mov_b32_e32 v50, v0
	v_mov_b32_e32 v51, v0
	v_mov_b32_e32 v52, v0
	v_mov_b32_e32 v53, v0
	v_mov_b32_e32 v54, v0
	v_mov_b32_e32 v55, v0
	v_mov_b32_e32 v56, v0
	v_mov_b32_e32 v57, v0
	v_mov_b32_e32 v58, v0
	v_mov_b32_e32 v59, v0
	v_mov_b32_e32 v60, v0
	v_mov_b32_e32 v61, v0
	v_mov_b32_e32 v62, v0
	v_mov_b32_e32 v63, v0
	v_mov_b32_e32 v64, v0
	v_mov_b32_e32 v65, v0
	v_mov_b32_e32 v66, v0
	v_mov_b32_e32 v67, v0
	v_mov_b32_e32 v68, v0
	v_mov_b32_e32 v69, v0
	v_mov_b32_e32 v70, v0
	v_mov_b32_e32 v71, v0
	v_mov_b32_e32 v72, v0
	v_mov_b32_e32 v73, v0
	v_mov_b32_e32 v74, v0
	v_mov_b32_e32 v75, v0
	v_mov_b32_e32 v76, v0
	v_mov_b32_e32 v77, v0
	v_mov_b32_e32 v78, v0
	v_mov_b32_e32 v79, v0
	v_mov_b32_e32 v80, v0
	v_mov_b32_e32 v81, v0
	v_mov_b32_e32 v82, v0
	v_mov_b32_e32 v83, v0
	v_mov_b32_e32 v84, v0
	v_mov_b32_e32 v85, v0
	v_mov_b32_e32 v86, v0
	v_mov_b32_e32 v87, v0
; #define WAIT_V(n) asm volatile("s_waitcnt vmcnt(" #n ")" ::: "memory")
; #define BAR __builtin_amdgcn_s_barrier()
;     ...
;   f32x4 acc[2][2][4][2] = {};
;   bf16x8 At[4][2], B0[2][2], B1[2][2];
;   const int nt = K / BK;
;   unsigned soff0, soff1;
;   { int _r, _c; stage_rc(tx * 16, _r, _c); soff0 = (unsigned)(_r * K + _c) * 2u;
;     stage_rc(tx * 16 + 8192, _r, _c); soff1 = (unsigned)(_r * K + _c) * 2u; }
;   STAGE(SB(0, 0), Bt, bcol, 0); STAGE(SA(0, 0), A, brow, 0);
;   STAGE(SB(0, 1), Bt, bcol1, 0); STAGE(SA(0, 1), A, brow + HALF, 0);
;   if (wr == 1) BAR;
;   WAIT_V(4); BAR;
;   STAGE(SB(1, 0), Bt, bcol, 1); STAGE(SA(1, 0), A, brow, 1); STAGE(SB(1, 1), Bt, bcol1, 1);
;   WAIT_V(6); BAR;
;   for (int t = 0; t < nt - 2; t += 2) {
	v_mov_b32_e32 v88, v0
	v_mov_b32_e32 v89, v0
	v_mov_b32_e32 v90, v0
	v_mov_b32_e32 v91, v0
	v_mov_b32_e32 v92, v0
	v_mov_b32_e32 v93, v0
	v_mov_b32_e32 v94, v0
	v_mov_b32_e32 v95, v0
	v_mov_b32_e32 v96, v0
	v_mov_b32_e32 v97, v0
	v_mov_b32_e32 v98, v0
	v_mov_b32_e32 v99, v0
	v_mov_b32_e32 v100, v0
	v_mov_b32_e32 v101, v0
	v_mov_b32_e32 v102, v0
	v_mov_b32_e32 v103, v0
	v_mov_b32_e32 v104, v0
	v_mov_b32_e32 v105, v0
	v_mov_b32_e32 v106, v0
	v_mov_b32_e32 v107, v0
	v_mov_b32_e32 v108, v0
	v_mov_b32_e32 v109, v0
	v_mov_b32_e32 v110, v0
	v_mov_b32_e32 v111, v0
	v_mov_b32_e32 v112, v0
	v_mov_b32_e32 v113, v0
	v_mov_b32_e32 v114, v0
	v_mov_b32_e32 v115, v0
	v_mov_b32_e32 v116, v0
	v_mov_b32_e32 v117, v0
	v_mov_b32_e32 v118, v0
	v_mov_b32_e32 v119, v0
	v_mov_b32_e32 v120, v0
	v_mov_b32_e32 v121, v0
	v_mov_b32_e32 v122, v0
	v_mov_b32_e32 v123, v0
	v_mov_b32_e32 v124, v0
	v_mov_b32_e32 v125, v0
	v_mov_b32_e32 v126, v0
	v_mov_b32_e32 v127, v0
	v_readfirstlane_b32 s12, v154
	v_writelane_b32 v254, s64, 0
	v_writelane_b32 v254, s65, 1
	v_writelane_b32 v254, s66, 2
	v_writelane_b32 v254, s67, 3
	v_writelane_b32 v254, s68, 4
	v_writelane_b32 v254, s69, 5
	v_writelane_b32 v254, s70, 6
	v_writelane_b32 v254, s71, 7
	v_writelane_b32 v254, s72, 8
	v_writelane_b32 v254, s73, 9
	v_writelane_b32 v254, s74, 10
	v_writelane_b32 v254, s75, 11
	v_writelane_b32 v254, s76, 12
	v_writelane_b32 v254, s77, 13
	v_writelane_b32 v254, s78, 14
	v_writelane_b32 v254, s79, 15
	v_writelane_b32 v254, s80, 16
	v_writelane_b32 v254, s81, 17
	v_writelane_b32 v254, s82, 18
	v_writelane_b32 v254, s83, 19
	v_writelane_b32 v254, s84, 20
	v_writelane_b32 v254, s85, 21
	v_writelane_b32 v254, s86, 22
	v_writelane_b32 v254, s87, 23
	v_writelane_b32 v254, s88, 24
	v_writelane_b32 v254, s89, 25
	v_writelane_b32 v254, s90, 26
	v_writelane_b32 v254, s91, 27
	v_writelane_b32 v254, s92, 28
	v_writelane_b32 v254, s93, 29
	v_writelane_b32 v254, s94, 30
	v_writelane_b32 v254, s95, 31
	v_readfirstlane_b32 s64, v134
	v_readfirstlane_b32 s65, v135
	v_readfirstlane_b32 s66, v136
	v_readfirstlane_b32 s67, v137
	v_readfirstlane_b32 s68, v130
	v_readfirstlane_b32 s69, v131
	v_readfirstlane_b32 s70, v132
	v_readfirstlane_b32 s71, v133
	v_readfirstlane_b32 s72, v134
	v_readfirstlane_b32 s73, v135
	v_readfirstlane_b32 s74, v136
	v_readfirstlane_b32 s75, v137
	v_readfirstlane_b32 s76, v138
	v_readfirstlane_b32 s77, v139
	v_readfirstlane_b32 s78, v140
	v_readfirstlane_b32 s79, v141
	v_readfirstlane_b32 s80, v134
	v_readfirstlane_b32 s81, v135
	v_readfirstlane_b32 s82, v136
	v_readfirstlane_b32 s83, v137
	v_readfirstlane_b32 s84, v130
	v_readfirstlane_b32 s85, v131
	v_readfirstlane_b32 s86, v132
	v_readfirstlane_b32 s87, v133
	v_readfirstlane_b32 s88, v134
	v_readfirstlane_b32 s89, v135
	v_readfirstlane_b32 s90, v136
	v_readfirstlane_b32 s91, v137
	v_readfirstlane_b32 s92, v138
	v_readfirstlane_b32 s93, v139
	v_readfirstlane_b32 s94, v140
	v_readfirstlane_b32 s95, v141
	s_nop 3
	v_subrev_u32_e32 v159, s64, v134
	v_subrev_u32_e32 v160, s66, v136
	v_subrev_u32_e32 v157, s68, v130
	v_subrev_u32_e32 v158, s70, v132
	v_subrev_u32_e32 v162, s76, v138
	v_subrev_u32_e32 v163, s78, v140
	s_add_u32 s64, s64, s4
	s_addc_u32 s65, s65, s5
	s_add_u32 s64, s64, s24
	s_addc_u32 s65, s65, s25
	s_add_u32 s66, s66, s4
	s_addc_u32 s67, s67, s5
	s_add_u32 s66, s66, s24
	s_addc_u32 s67, s67, s25
	s_add_u32 s68, s68, s4
	s_addc_u32 s69, s69, s5
	s_add_u32 s68, s68, s26
	s_addc_u32 s69, s69, s27
	s_add_u32 s70, s70, s4
	s_addc_u32 s71, s71, s5
	s_add_u32 s70, s70, s26
	s_addc_u32 s71, s71, s27
	s_add_u32 s72, s72, s4
	s_addc_u32 s73, s73, s5
	s_add_u32 s72, s72, s26
	s_addc_u32 s73, s73, s27
	s_add_u32 s74, s74, s4
	s_addc_u32 s75, s75, s5
	s_add_u32 s74, s74, s26
	s_addc_u32 s75, s75, s27
	s_add_u32 s76, s76, s4
	s_addc_u32 s77, s77, s5
	s_add_u32 s76, s76, s28
	s_addc_u32 s77, s77, s29
	s_add_u32 s78, s78, s4
	s_addc_u32 s79, s79, s5
	s_add_u32 s78, s78, s28
	s_addc_u32 s79, s79, s29
	s_add_u32 s80, s80, s4
	s_addc_u32 s81, s81, s5
	s_add_u32 s80, s80, s30
	s_addc_u32 s81, s81, s31
	s_add_u32 s82, s82, s4
	s_addc_u32 s83, s83, s5
	s_add_u32 s82, s82, s30
	s_addc_u32 s83, s83, s31
	s_add_u32 s84, s84, s4
	s_addc_u32 s85, s85, s5
	s_add_u32 s84, s84, s34
	s_addc_u32 s85, s85, s35
	s_add_u32 s86, s86, s4
	s_addc_u32 s87, s87, s5
	s_add_u32 s86, s86, s34
	s_addc_u32 s87, s87, s35
	s_add_u32 s88, s88, s4
	s_addc_u32 s89, s89, s5
	s_add_u32 s88, s88, s34
	s_addc_u32 s89, s89, s35
	s_add_u32 s90, s90, s4
	s_addc_u32 s91, s91, s5
	s_add_u32 s90, s90, s34
	s_addc_u32 s91, s91, s35
	s_add_u32 s92, s92, s4
	s_addc_u32 s93, s93, s5
	s_add_u32 s92, s92, s36
	s_addc_u32 s93, s93, s37
	s_add_u32 s94, s94, s4
	s_addc_u32 s95, s95, s5
	s_add_u32 s94, s94, s36
	s_addc_u32 s95, s95, s37
	v_add_u32_e32 v174, 0xc000, v154
	v_add_u32_e32 v175, 0xe000, v154
	s_waitcnt vmcnt(6)
	s_barrier

; #define WAIT_V(n) asm volatile("s_waitcnt vmcnt(" #n ")" ::: "memory")
; #define BAR __builtin_amdgcn_s_barrier()
;     ...
;   const int wid = tx >> 6, lane = tx & 63, wr = wid >> 2, wc = wid & 3, fr = lane & 15, fq = lane >> 4;
;   f32x4 acc[2][2][4][2] = {};
;   bf16x8 At[4][2], B0[2][2], B1[2][2];
;   const int nt = K / BK;
;   unsigned soff0, soff1;
;   { int _r, _c; stage_rc(tx * 16, _r, _c); soff0 = (unsigned)(_r * K + _c) * 2u;
;     stage_rc(tx * 16 + 8192, _r, _c); soff1 = (unsigned)(_r * K + _c) * 2u; }
;   STAGE(SB(0, 0), Bt, bcol, 0); STAGE(SA(0, 0), A, brow, 0);
;   STAGE(SB(0, 1), Bt, bcol1, 0); STAGE(SA(0, 1), A, brow + HALF, 0);
;   if (wr == 1) BAR;
;   WAIT_V(4); BAR;
;   STAGE(SB(1, 0), Bt, bcol, 1); STAGE(SA(1, 0), A, brow, 1); STAGE(SB(1, 1), Bt, bcol1, 1);
;   WAIT_V(6); BAR;
.LBB0_1334:
	s_or_b64 exec, exec, s[22:23]
	v_add_u32_e32 v162, s59, v15
	v_add_u32_e32 v163, 0x2000, v162
	v_readfirstlane_b32 s22, v162
	v_lshl_add_u64 v[6:7], v[6:7], 0, s[10:11]
	s_mov_b32 m0, s22
	v_readfirstlane_b32 s22, v163
	v_add_u32_e32 v164, 0x8000, v155
	s_waitcnt vmcnt(4)
	s_barrier
	global_load_lds_dwordx4 v[6:7], off
	v_lshl_add_u64 v[4:5], v[4:5], 0, s[10:11]
	s_mov_b32 m0, s22
	v_readfirstlane_b32 s22, v164
	v_add_u32_e32 v165, 0xa000, v155
	global_load_lds_dwordx4 v[4:5], off
	v_lshl_add_u64 v[2:3], v[2:3], 0, s[10:11]
	s_mov_b32 m0, s22
	v_readfirstlane_b32 s22, v165
	s_add_u32 s6, s6, 0x2b0080
	v_add_u32_e32 v166, s60, v15
	global_load_lds_dwordx4 v[2:3], off
	v_lshl_add_u64 v[0:1], v[0:1], 0, s[10:11]
	s_mov_b32 m0, s22
	s_addc_u32 s7, s7, 0
	v_readfirstlane_b32 s22, v166
	global_load_lds_dwordx4 v[0:1], off
	v_lshl_add_u64 v[0:1], s[6:7], 0, v[128:129]
	s_mov_b32 m0, s22
	v_add_u32_e32 v167, 0x2000, v166
	global_load_lds_dwordx4 v[0:1], off
	v_lshl_add_u64 v[0:1], s[6:7], 0, v[130:131]
	v_readfirstlane_b32 s6, v167
	s_mov_b32 m0, s6
	v_and_b32_e32 v142, 15, v140
	global_load_lds_dwordx4 v[0:1], off
	v_lshlrev_b32_e32 v2, 2, v140
	v_and_b32_e32 v0, 48, v140
	v_lshlrev_b32_e32 v1, 6, v142
	v_and_b32_e32 v2, 32, v2
	v_bitop3_b32 v1, v1, v2, v0 bitop3:0x36
	v_add_u32_e32 v5, s33, v1
	v_add_u32_e32 v6, s58, v1
	v_add_u32_e32 v7, s59, v1
	v_add_u32_e32 v15, s60, v1
	v_add_u32_e32 v18, 0, v1
	v_lshlrev_b32_e32 v1, 6, v140
	v_and_or_b32 v0, v1, s28, v0
	v_xad_u32 v19, v0, v2, 0
	v_lshrrev_b32_e32 v1, 1, v8
	v_mul_lo_u32 v0, v9, s27
	v_lshrrev_b32_e32 v3, 1, v12
	v_mul_lo_u32 v2, v13, s27
	v_mad_u64_u32 v[0:1], s[6:7], v1, s29, v[0:1]
	v_mad_u64_u32 v[2:3], s[22:23], v3, s29, v[2:3]
	v_or_b32_e32 v0, v0, v10
	s_add_u32 s6, s0, s37
	v_or_b32_e32 v2, v2, v14
	v_add_lshl_u32 v0, v0, v11, 1
	v_mov_b32_e32 v1, v129
	s_addc_u32 s7, s1, s38
	v_add_lshl_u32 v2, v2, v16, 1
	v_mov_b32_e32 v3, v129
	v_lshl_add_u64 v[132:133], s[6:7], 0, v[0:1]
	v_lshl_add_u64 v[134:135], s[6:7], 0, v[2:3]
	s_add_i32 s6, s35, s36
	s_mul_hi_i32 s7, s6, 0x5600
	s_mulk_i32 s6, 0x5600
	s_add_u32 s6, s2, s6
	v_bfe_u32 v141, v148, 6, 2
	v_lshlrev_b32_e32 v143, 6, v17
	v_lshlrev_b32_e32 v17, 13, v17
	s_addc_u32 s7, s3, s7
	v_lshlrev_b32_e32 v4, 12, v141
	v_or_b32_e32 v20, 0x800, v17
	v_or_b32_e32 v21, 0x1000, v17
	v_or_b32_e32 v22, 0x1800, v17
	v_lshl_add_u64 v[136:137], s[6:7], 0, v[0:1]
	v_mov_b32_e32 v0, 0
	v_or_b32_e32 v149, v143, v142
	v_lshl_add_u64 v[138:139], s[6:7], 0, v[2:3]
	s_mov_b32 s22, -2
	s_mov_b64 s[6:7], 0
	v_add_u32_e32 v169, v5, v4
	v_add_u32_e32 v151, v18, v17
	v_add_u32_e32 v150, v19, v20
	v_add_u32_e32 v145, v19, v21
	v_add_u32_e32 v144, v19, v22
	v_add_u32_e32 v168, v6, v4
	v_add_u32_e32 v160, v7, v4
	v_add_u32_e32 v154, v15, v4
	v_mov_b32_e32 v1, v0
	v_mov_b32_e32 v2, v0
	v_mov_b32_e32 v3, v0
	v_mov_b32_e32 v4, v0
	v_mov_b32_e32 v5, v0
	v_mov_b32_e32 v6, v0
	v_mov_b32_e32 v7, v0
	v_mov_b32_e32 v8, v0
	v_mov_b32_e32 v9, v0
	v_mov_b32_e32 v10, v0
	v_mov_b32_e32 v11, v0
	v_mov_b32_e32 v12, v0
	v_mov_b32_e32 v13, v0
	v_mov_b32_e32 v14, v0
	v_mov_b32_e32 v15, v0
	v_mov_b32_e32 v16, v0
	v_mov_b32_e32 v17, v0
	v_mov_b32_e32 v18, v0
	v_mov_b32_e32 v19, v0
	v_mov_b32_e32 v20, v0
	v_mov_b32_e32 v21, v0
	v_mov_b32_e32 v22, v0
	v_mov_b32_e32 v23, v0
	v_mov_b32_e32 v24, v0
	v_mov_b32_e32 v25, v0
	v_mov_b32_e32 v26, v0
	v_mov_b32_e32 v27, v0
	v_mov_b32_e32 v28, v0
	v_mov_b32_e32 v29, v0
	v_mov_b32_e32 v30, v0
	v_mov_b32_e32 v31, v0
	v_mov_b32_e32 v32, v0
	v_mov_b32_e32 v33, v0
	v_mov_b32_e32 v34, v0
	v_mov_b32_e32 v35, v0
	v_mov_b32_e32 v36, v0
	v_mov_b32_e32 v37, v0
	v_mov_b32_e32 v38, v0
	v_mov_b32_e32 v39, v0
	v_mov_b32_e32 v40, v0
	v_mov_b32_e32 v41, v0
	v_mov_b32_e32 v42, v0
	v_mov_b32_e32 v43, v0
	v_mov_b32_e32 v44, v0
	v_mov_b32_e32 v45, v0
	v_mov_b32_e32 v46, v0
	v_mov_b32_e32 v47, v0
	v_mov_b32_e32 v48, v0
	v_mov_b32_e32 v49, v0
	v_mov_b32_e32 v50, v0
	v_mov_b32_e32 v51, v0
	v_mov_b32_e32 v52, v0
	v_mov_b32_e32 v53, v0
	v_mov_b32_e32 v54, v0
	v_mov_b32_e32 v55, v0
	v_mov_b32_e32 v56, v0
	v_mov_b32_e32 v57, v0
	v_mov_b32_e32 v58, v0
	v_mov_b32_e32 v59, v0
	v_mov_b32_e32 v60, v0
	v_mov_b32_e32 v61, v0
	v_mov_b32_e32 v62, v0
	v_mov_b32_e32 v63, v0
	v_mov_b32_e32 v64, v0
	v_mov_b32_e32 v65, v0
	v_mov_b32_e32 v66, v0
	v_mov_b32_e32 v67, v0
	v_mov_b32_e32 v68, v0
	v_mov_b32_e32 v69, v0
	v_mov_b32_e32 v70, v0
	v_mov_b32_e32 v71, v0
	v_mov_b32_e32 v72, v0
	v_mov_b32_e32 v73, v0
	v_mov_b32_e32 v74, v0
	v_mov_b32_e32 v75, v0
	v_mov_b32_e32 v76, v0
	v_mov_b32_e32 v77, v0
	v_mov_b32_e32 v78, v0
	v_mov_b32_e32 v79, v0
	v_mov_b32_e32 v80, v0
	v_mov_b32_e32 v81, v0
	v_mov_b32_e32 v82, v0
	v_mov_b32_e32 v83, v0
	v_mov_b32_e32 v84, v0
	v_mov_b32_e32 v85, v0
	v_mov_b32_e32 v86, v0
	v_mov_b32_e32 v87, v0
	v_mov_b32_e32 v88, v0
; #define WAIT_V(n) asm volatile("s_waitcnt vmcnt(" #n ")" ::: "memory")
; #define BAR __builtin_amdgcn_s_barrier()
;     ...
;   f32x4 acc[2][2][4][2] = {};
;   bf16x8 At[4][2], B0[2][2], B1[2][2];
;   const int nt = K / BK;
;   unsigned soff0, soff1;
;   { int _r, _c; stage_rc(tx * 16, _r, _c); soff0 = (unsigned)(_r * K + _c) * 2u;
;     stage_rc(tx * 16 + 8192, _r, _c); soff1 = (unsigned)(_r * K + _c) * 2u; }
;   STAGE(SB(0, 0), Bt, bcol, 0); STAGE(SA(0, 0), A, brow, 0);
;   STAGE(SB(0, 1), Bt, bcol1, 0); STAGE(SA(0, 1), A, brow + HALF, 0);
;   if (wr == 1) BAR;
;   WAIT_V(4); BAR;
;   STAGE(SB(1, 0), Bt, bcol, 1); STAGE(SA(1, 0), A, brow, 1); STAGE(SB(1, 1), Bt, bcol1, 1);
;   WAIT_V(6); BAR;
;   for (int t = 0; t < nt - 2; t += 2) {
	v_mov_b32_e32 v89, v0
	v_mov_b32_e32 v90, v0
	v_mov_b32_e32 v91, v0
	v_mov_b32_e32 v92, v0
	v_mov_b32_e32 v93, v0
	v_mov_b32_e32 v94, v0
	v_mov_b32_e32 v95, v0
	v_mov_b32_e32 v96, v0
	v_mov_b32_e32 v97, v0
	v_mov_b32_e32 v98, v0
	v_mov_b32_e32 v99, v0
	v_mov_b32_e32 v100, v0
	v_mov_b32_e32 v101, v0
	v_mov_b32_e32 v102, v0
	v_mov_b32_e32 v103, v0
	v_mov_b32_e32 v104, v0
	v_mov_b32_e32 v105, v0
	v_mov_b32_e32 v106, v0
	v_mov_b32_e32 v107, v0
	v_mov_b32_e32 v108, v0
	v_mov_b32_e32 v109, v0
	v_mov_b32_e32 v110, v0
	v_mov_b32_e32 v111, v0
	v_mov_b32_e32 v112, v0
	v_mov_b32_e32 v113, v0
	v_mov_b32_e32 v114, v0
	v_mov_b32_e32 v115, v0
	v_mov_b32_e32 v116, v0
	v_mov_b32_e32 v117, v0
	v_mov_b32_e32 v118, v0
	v_mov_b32_e32 v119, v0
	v_mov_b32_e32 v120, v0
	v_mov_b32_e32 v121, v0
	v_mov_b32_e32 v122, v0
	v_mov_b32_e32 v123, v0
	v_mov_b32_e32 v124, v0
	v_mov_b32_e32 v125, v0
	v_mov_b32_e32 v126, v0
	v_mov_b32_e32 v127, v0
	v_readfirstlane_b32 s23, v155
	v_writelane_b32 v254, s64, 0
	v_writelane_b32 v254, s65, 1
	v_writelane_b32 v254, s66, 2
	v_writelane_b32 v254, s67, 3
	v_writelane_b32 v254, s68, 4
	v_writelane_b32 v254, s69, 5
	v_writelane_b32 v254, s70, 6
	v_writelane_b32 v254, s71, 7
	v_writelane_b32 v254, s72, 8
	v_writelane_b32 v254, s73, 9
	v_writelane_b32 v254, s74, 10
	v_writelane_b32 v254, s75, 11
	v_writelane_b32 v254, s76, 12
	v_writelane_b32 v254, s77, 13
	v_writelane_b32 v254, s78, 14
	v_writelane_b32 v254, s79, 15
	v_writelane_b32 v254, s80, 16
	v_writelane_b32 v254, s81, 17
	v_writelane_b32 v254, s82, 18
	v_writelane_b32 v254, s83, 19
	v_writelane_b32 v254, s84, 20
	v_writelane_b32 v254, s85, 21
	v_writelane_b32 v254, s86, 22
	v_writelane_b32 v254, s87, 23
	v_writelane_b32 v254, s88, 24
	v_writelane_b32 v254, s89, 25
	v_writelane_b32 v254, s90, 26
	v_writelane_b32 v254, s91, 27
	v_writelane_b32 v254, s92, 28
	v_writelane_b32 v254, s93, 29
	v_writelane_b32 v254, s94, 30
	v_writelane_b32 v254, s95, 31
	v_readfirstlane_b32 s64, v136
	v_readfirstlane_b32 s65, v137
	v_readfirstlane_b32 s66, v138
	v_readfirstlane_b32 s67, v139
	v_readfirstlane_b32 s68, v132
	v_readfirstlane_b32 s69, v133
	v_readfirstlane_b32 s70, v134
	v_readfirstlane_b32 s71, v135
	v_readfirstlane_b32 s72, v136
	v_readfirstlane_b32 s73, v137
	v_readfirstlane_b32 s74, v138
	v_readfirstlane_b32 s75, v139
	v_readfirstlane_b32 s76, v132
	v_readfirstlane_b32 s77, v133
	v_readfirstlane_b32 s78, v134
	v_readfirstlane_b32 s79, v135
	v_readfirstlane_b32 s80, v136
	v_readfirstlane_b32 s81, v137
	v_readfirstlane_b32 s82, v138
	v_readfirstlane_b32 s83, v139
	v_readfirstlane_b32 s84, v132
	v_readfirstlane_b32 s85, v133
	v_readfirstlane_b32 s86, v134
	v_readfirstlane_b32 s87, v135
	v_readfirstlane_b32 s88, v136
	v_readfirstlane_b32 s89, v137
	v_readfirstlane_b32 s90, v138
	v_readfirstlane_b32 s91, v139
	v_readfirstlane_b32 s92, v132
	v_readfirstlane_b32 s93, v133
	v_readfirstlane_b32 s94, v134
	v_readfirstlane_b32 s95, v135
	s_nop 3
	v_subrev_u32_e32 v158, s64, v136
	v_subrev_u32_e32 v159, s66, v138
	v_subrev_u32_e32 v156, s68, v132
	v_subrev_u32_e32 v157, s70, v134
	s_add_u32 s64, s64, s6
	s_addc_u32 s65, s65, s7
	s_add_u32 s64, s64, s12
	s_addc_u32 s65, s65, s13
	s_add_u32 s66, s66, s6
	s_addc_u32 s67, s67, s7
	s_add_u32 s66, s66, s12
	s_addc_u32 s67, s67, s13
	s_add_u32 s68, s68, s6
	s_addc_u32 s69, s69, s7
	s_add_u32 s68, s68, s14
	s_addc_u32 s69, s69, s15
	s_add_u32 s70, s70, s6
	s_addc_u32 s71, s71, s7
	s_add_u32 s70, s70, s14
	s_addc_u32 s71, s71, s15
	s_add_u32 s72, s72, s6
	s_addc_u32 s73, s73, s7
	s_add_u32 s72, s72, s14
	s_addc_u32 s73, s73, s15
	s_add_u32 s74, s74, s6
	s_addc_u32 s75, s75, s7
	s_add_u32 s74, s74, s14
	s_addc_u32 s75, s75, s15
	s_add_u32 s76, s76, s6
	s_addc_u32 s77, s77, s7
	s_add_u32 s76, s76, s16
	s_addc_u32 s77, s77, s17
	s_add_u32 s78, s78, s6
	s_addc_u32 s79, s79, s7
	s_add_u32 s78, s78, s16
	s_addc_u32 s79, s79, s17
	s_add_u32 s80, s80, s6
	s_addc_u32 s81, s81, s7
	s_add_u32 s80, s80, s16
	s_addc_u32 s81, s81, s17
	s_add_u32 s82, s82, s6
	s_addc_u32 s83, s83, s7
	s_add_u32 s82, s82, s16
	s_addc_u32 s83, s83, s17
	s_add_u32 s84, s84, s6
	s_addc_u32 s85, s85, s7
	s_add_u32 s84, s84, s18
	s_addc_u32 s85, s85, s19
	s_add_u32 s86, s86, s6
	s_addc_u32 s87, s87, s7
	s_add_u32 s86, s86, s18
	s_addc_u32 s87, s87, s19
	s_add_u32 s88, s88, s6
	s_addc_u32 s89, s89, s7
	s_add_u32 s88, s88, s18
	s_addc_u32 s89, s89, s19
	s_add_u32 s90, s90, s6
	s_addc_u32 s91, s91, s7
	s_add_u32 s90, s90, s18
	s_addc_u32 s91, s91, s19
	s_add_u32 s92, s92, s6
	s_addc_u32 s93, s93, s7
	s_add_u32 s92, s92, s20
	s_addc_u32 s93, s93, s21
	s_add_u32 s94, s94, s6
	s_addc_u32 s95, s95, s7
	s_add_u32 s94, s94, s20
	s_addc_u32 s95, s95, s21
	v_add_u32_e32 v170, 0xc000, v155
	v_add_u32_e32 v171, 0xe000, v155
	s_waitcnt vmcnt(6)
	s_barrier
